# layer-1 RMSNorm row loop: all four x loads issued together (partial-sum temporaries renamed) and all gain/shift/scale vector loads of the row issued at the top of the iteration into spare registers, o
# speedup vs baseline: 1.0122x; 1.0122x over previous
.LBB0_586:
	v_add_u32_e32 v18, s2, v49
	v_ashrrev_i32_e32 v19, 31, v18
	v_lshlrev_b64 v[2:3], 12, v[18:19]
	v_lshl_add_u64 v[2:3], v[24:25], 0, v[2:3]
	global_load_dwordx4 v[14:17], v[2:3], off
	global_load_dwordx4 v[10:13], v[2:3], off offset:1024
	global_load_dwordx4 v[6:9], v[2:3], off offset:2048
	s_nop 0
	global_load_dwordx4 v[2:5], v[2:3], off offset:3072
	v_mov_b32_e32 v29, v0
	v_mov_b32_e32 v31, v0
	v_mov_b32_e32 v33, v0
	v_mov_b32_e32 v35, v0
	v_cmp_lt_i32_e32 vcc, s43, v18
	s_nop 1
	v_cndmask_b32_e32 v112, v187, v1, vcc
	v_ashrrev_i32_e32 v113, 31, v112
	v_lshl_add_u64 v[112:113], v[112:113], 2, s[4:5]
	v_lshl_add_u64 v[114:115], v[112:113], 0, s[8:9]
	v_lshl_add_u64 v[116:117], v[112:113], 0, v[28:29]
	global_load_dwordx4 v[80:83], v[116:117], off
	global_load_dwordx4 v[84:87], v[116:117], off offset:1024
	global_load_dwordx4 v[88:91], v[116:117], off offset:2048
	global_load_dwordx4 v[92:95], v[116:117], off offset:3072
	v_lshl_add_u64 v[118:119], v[114:115], 0, v[28:29]
	global_load_dwordx4 v[96:99], v[118:119], off
	v_lshl_add_u64 v[118:119], v[114:115], 0, v[30:31]
	global_load_dwordx4 v[100:103], v[118:119], off
	v_lshl_add_u64 v[118:119], v[114:115], 0, v[32:33]
	global_load_dwordx4 v[104:107], v[118:119], off
	v_lshl_add_u64 v[118:119], v[114:115], 0, v[34:35]
	global_load_dwordx4 v[108:111], v[118:119], off
	global_load_dwordx4 v[68:71], v[22:23], off offset:1024
	global_load_dwordx4 v[72:75], v[22:23], off offset:2048
	global_load_dwordx4 v[76:79], v[22:23], off offset:3072
	s_add_i32 s2, s2, 1
	s_cmp_lg_u32 s2, 4
	s_waitcnt vmcnt(14)
	s_waitcnt vmcnt(13)
	v_mul_f32_e32 v249, v15, v15
	v_mul_f32_e32 v250, v11, v11
	s_nop 0
	v_fma_f32 v251, v14, v14, v249
	v_fma_f32 v252, v10, v10, v250
	v_fma_f32 v251, v16, v16, v251
	v_fma_f32 v252, v12, v12, v252
	v_fma_f32 v20, v17, v17, v251
	v_fma_f32 v21, v13, v13, v252
	v_add_f32_e32 v20, v20, v21
	global_load_dwordx4 v[50:53], v[22:23], off
	s_waitcnt vmcnt(13)
	s_waitcnt vmcnt(12)
	v_mul_f32_e32 v40, v7, v7
	v_mul_f32_e32 v41, v3, v3
	s_nop 0
	v_fma_f32 v38, v6, v6, v40
	v_fma_f32 v39, v2, v2, v41
	v_fma_f32 v38, v8, v8, v38
	v_fma_f32 v39, v4, v4, v39
	v_fma_f32 v38, v9, v9, v38
	v_fma_f32 v39, v5, v5, v39
	s_nop 0
	v_add_f32_e32 v20, v20, v38
	v_add_f32_e32 v20, v20, v39
	ds_bpermute_b32 v21, v37, v20
	s_nop 2
	s_waitcnt lgkmcnt(0)
	v_add_f32_e32 v20, v20, v21
	ds_bpermute_b32 v21, v44, v20
	s_nop 2
	s_waitcnt lgkmcnt(0)
	v_add_f32_e32 v20, v20, v21
	ds_bpermute_b32 v21, v45, v20
	s_nop 2
	s_waitcnt lgkmcnt(0)
	v_add_f32_e32 v20, v20, v21
	ds_bpermute_b32 v21, v46, v20
	s_nop 2
	s_waitcnt lgkmcnt(0)
	v_add_f32_e32 v20, v20, v21
	ds_bpermute_b32 v21, v47, v20
	s_nop 2
	s_waitcnt lgkmcnt(0)
	v_add_f32_e32 v20, v20, v21
	ds_bpermute_b32 v21, v48, v20
	s_waitcnt lgkmcnt(0)
	v_add_f32_e32 v20, v20, v21
	v_fmamk_f32 v20, v20, 0x3a800000, v188
	v_cmp_gt_f32_e32 vcc, s6, v20
	s_nop 2
	v_mul_f32_e32 v21, 0x4b800000, v20
	s_nop 0
	v_cndmask_b32_e32 v20, v20, v21, vcc
	v_rsq_f32_e32 v20, v20
	s_nop 0
	v_mul_f32_e32 v21, 0x45800000, v20
	v_cndmask_b32_e32 v36, v20, v21, vcc
	v_cmp_lt_i32_e32 vcc, s43, v18
	v_pk_mul_f32 v[14:15], v[14:15], v[36:37] op_sel_hi:[1,0]
	v_pk_mul_f32 v[16:17], v[16:17], v[36:37] op_sel_hi:[1,0]
	v_cndmask_b32_e32 v20, v187, v1, vcc
	v_ashrrev_i32_e32 v21, 31, v20
	v_lshl_add_u64 v[20:21], v[20:21], 2, s[4:5]
	v_lshl_add_u64 v[38:39], v[20:21], 0, s[8:9]
	v_lshl_add_u64 v[42:43], v[20:21], 0, v[28:29]
	v_lshl_add_u64 v[20:21], v[38:39], 0, v[28:29]
	s_waitcnt vmcnt(0)
	v_pk_mul_f32 v[14:15], v[50:51], v[14:15]
	v_pk_mul_f32 v[16:17], v[52:53], v[16:17]
	v_lshlrev_b64 v[18:19], 11, v[18:19]
	v_lshl_add_u64 v[40:41], v[26:27], 0, v[18:19]
	v_lshl_add_u64 v[50:51], v[38:39], 0, v[30:31]
	v_pk_mul_f32 v[10:11], v[10:11], v[36:37] op_sel_hi:[1,0]
	v_pk_mul_f32 v[12:13], v[12:13], v[36:37] op_sel_hi:[1,0]
	v_pk_mul_f32 v[6:7], v[6:7], v[36:37] op_sel_hi:[1,0]
	v_pk_mul_f32 v[8:9], v[8:9], v[36:37] op_sel_hi:[1,0]
	v_pk_mul_f32 v[2:3], v[2:3], v[36:37] op_sel_hi:[1,0]
	v_pk_mul_f32 v[4:5], v[4:5], v[36:37] op_sel_hi:[1,0]
	s_nop 0
	v_pk_add_f32 v[20:21], v[96:97], 1.0 op_sel_hi:[1,0]
	s_nop 0
	v_pk_fma_f32 v[14:15], v[20:21], v[14:15], v[80:81]
	v_pk_add_f32 v[20:21], v[98:99], 1.0 op_sel_hi:[1,0]
	v_cvt_pk_bf16_f32 v14, v14, v15
	v_pk_fma_f32 v[16:17], v[20:21], v[16:17], v[82:83]
	s_nop 0
	v_cvt_pk_bf16_f32 v15, v16, v17
	global_store_dwordx2 v[40:41], v[14:15], off
	v_pk_mul_f32 v[10:11], v[68:69], v[10:11]
	v_pk_mul_f32 v[12:13], v[70:71], v[12:13]
	v_pk_add_f32 v[120:121], v[100:101], 1.0 op_sel_hi:[1,0]
	v_pk_add_f32 v[122:123], v[102:103], 1.0 op_sel_hi:[1,0]
	v_pk_fma_f32 v[10:11], v[120:121], v[10:11], v[84:85]
	v_pk_fma_f32 v[12:13], v[122:123], v[12:13], v[86:87]
	s_nop 0
	v_cvt_pk_bf16_f32 v10, v10, v11
	v_cvt_pk_bf16_f32 v11, v12, v13
	global_store_dwordx2 v[40:41], v[10:11], off offset:512
	v_pk_mul_f32 v[6:7], v[72:73], v[6:7]
	v_pk_mul_f32 v[8:9], v[74:75], v[8:9]
	v_pk_add_f32 v[120:121], v[104:105], 1.0 op_sel_hi:[1,0]
	v_pk_add_f32 v[122:123], v[106:107], 1.0 op_sel_hi:[1,0]
	v_pk_fma_f32 v[6:7], v[120:121], v[6:7], v[88:89]
	v_pk_fma_f32 v[8:9], v[122:123], v[8:9], v[90:91]
	s_nop 0
	v_cvt_pk_bf16_f32 v6, v6, v7
	v_cvt_pk_bf16_f32 v7, v8, v9
	global_store_dwordx2 v[40:41], v[6:7], off offset:1024
	v_pk_mul_f32 v[2:3], v[76:77], v[2:3]
	v_pk_mul_f32 v[4:5], v[78:79], v[4:5]
	v_pk_add_f32 v[120:121], v[108:109], 1.0 op_sel_hi:[1,0]
	v_pk_add_f32 v[122:123], v[110:111], 1.0 op_sel_hi:[1,0]
	v_pk_fma_f32 v[2:3], v[120:121], v[2:3], v[92:93]
	v_pk_fma_f32 v[4:5], v[122:123], v[4:5], v[94:95]
	s_nop 0
	v_cvt_pk_bf16_f32 v2, v2, v3
	v_cvt_pk_bf16_f32 v3, v4, v5
	global_store_dwordx2 v[40:41], v[2:3], off offset:1536
	s_cbranch_scc1 .LBB0_586
	v_readlane_b32 s2, v245, 36
	s_add_i32 s1, s1, s94
	s_add_i32 s0, s0, s2
	s_cmpk_gt_i32 s1, 0x9ff
	s_cbranch_scc0 .LBB0_585
